# out-projection epilogue: the once-read f32 residual (x) base loads carry the nt hint
# speedup vs baseline: 1.0156x; 1.0008x over previous
;     static __device__ __forceinline__ f32x4 ldb(const void* base, size_t idx) { if (MODE == 0) return *(const f32x4*)((const float*)base + idx); const u32x2 w = *(const u32x2*)((const bf16_t*)base + idx); return (f32x4){bflo(w.x), bfhi(w.x), bflo(w.y), bfhi(w.y)}; }
;     __device__ __forceinline__ void operator()(const f32x4 (&acc)[2][2][4][2], const Unit& u, int wr, int wc, int fr, int fq) const {
;     ...
;         const float* gp0 = gate + (size_t)((u.pm * BM) >> 11) * NMOD + col0;
;         f32x4 gt[2][2];
; #pragma unroll
;         for (int bj = 0; bj < 2; ++bj)
; #pragma unroll
;             for (int n = 0; n < 2; ++n) gt[bj][n] = *(const f32x4*)(gp0 + bj * HALF + n * 16);
; #pragma unroll
;         for (int ai = 0; ai < 2; ++ai)
; #pragma unroll
;           for (int mp = 0; mp < 2; ++mp) { f32x4 bb[2][2][2];
; #pragma unroll
;             for (int mm = 0; mm < 2; ++mm) { const size_t bi = (size_t)(row0 + ai * HALF + (2 * mp + mm) * 16) * DM + col0;
; #pragma unroll
;                 for (int bj = 0; bj < 2; ++bj)
; #pragma unroll
;                     for (int n = 0; n < 2; ++n) bb[mm][bj][n] = ldb(baseP, bi + bj * HALF + n * 16); }
; #pragma unroll
;             for (int mm = 0; mm < 2; ++mm) { const int m = 2 * mp + mm; float s = 0.f;
; #pragma unroll
;                 for (int bj = 0; bj < 2; ++bj)
; #pragma unroll
;                     for (int n = 0; n < 2; ++n) { const f32x4 x = bb[mm][bj][n] + gt[bj][n] * acc[ai][bj][m][n]; s += (x[0] * x[0] + x[1] * x[1]) + (x[2] * x[2] + x[3] * x[3]); }
;                 s += __shfl_xor(s, 16); s += __shfl_xor(s, 32);
;                 if (fq == 0) P[(ai * HALF + wr * 64 + m * 16 + fr) * 4 + wc] = s; }
;             asm volatile("" ::: "memory"); }
.LBB0_1284:
	s_lshl_b32 s47, s14, 8
	v_mbcnt_lo_u32_b32 v164, -1, 0
	v_mbcnt_hi_u32_b32 v164, -1, v164
	s_add_i32 s8, s47, s29
	v_and_b32_e32 v235, 15, v164
	v_or_b32_e32 v198, s8, v235
	s_lshl_b32 s8, s76, 8
	v_readlane_b32 s9, v237, 10
	v_ashrrev_i32_e32 v236, 4, v164
	s_or_b32 s8, s8, s9
	v_lshl_add_u32 v200, v236, 2, s8
	s_mov_b64 s[12:13], -1
	s_cmp_lt_i32 s46, 0
	v_ashrrev_i32_e32 v201, 31, v200
	s_cbranch_scc0 .LBB0_1326
	s_ashr_i32 s8, s14, 3
	s_mul_i32 s71, s8, 0x6000
	s_mul_hi_i32 s69, s8, 0x6000
	s_add_u32 s12, s92, s71
	s_addc_u32 s13, s93, s69
	v_lshlrev_b64 v[226:227], 2, v[200:201]
	v_ashrrev_i32_e32 v199, 31, v198
	v_lshl_add_u64 v[162:163], s[12:13], 0, v[226:227]
	global_load_dwordx4 v[142:145], v[162:163], off
	global_load_dwordx4 v[138:141], v[162:163], off offset:64
	global_load_dwordx4 v[134:137], v[162:163], off offset:512
	global_load_dwordx4 v[130:133], v[162:163], off offset:576
	v_lshl_add_u64 v[226:227], s[20:21], 0, v[226:227]
	v_lshlrev_b64 v[162:163], 12, v[198:199]
	v_lshl_add_u64 v[162:163], v[226:227], 0, v[162:163]
	s_mov_b64 s[78:79], 0x10000
	s_mov_b64 s[80:81], 0x50000
	global_load_dwordx4 v[146:149], v[162:163], off nt
	global_load_dwordx4 v[150:153], v[162:163], off offset:64 nt
	global_load_dwordx4 v[154:157], v[162:163], off offset:512 nt
	global_load_dwordx4 v[158:161], v[162:163], off offset:576 nt
	v_lshl_add_u64 v[162:163], v[162:163], 0, s[78:79]
	global_load_dwordx4 v[166:169], v[162:163], off nt
	global_load_dwordx4 v[170:173], v[162:163], off offset:64 nt
	global_load_dwordx4 v[174:177], v[162:163], off offset:512 nt
	global_load_dwordx4 v[178:181], v[162:163], off offset:576 nt
	v_lshl_add_u64 v[162:163], v[162:163], 0, s[78:79]
	global_load_dwordx4 v[182:185], v[162:163], off nt
	global_load_dwordx4 v[202:205], v[162:163], off offset:64 nt
	global_load_dwordx4 v[206:209], v[162:163], off offset:512 nt
	global_load_dwordx4 v[210:213], v[162:163], off offset:576 nt
	v_lshl_add_u64 v[162:163], v[162:163], 0, s[78:79]
	global_load_dwordx4 v[214:217], v[162:163], off nt
	global_load_dwordx4 v[218:221], v[162:163], off offset:64 nt
	global_load_dwordx4 v[238:241], v[162:163], off offset:512 nt
	global_load_dwordx4 v[242:245], v[162:163], off offset:576 nt
	v_lshl_add_u64 v[162:163], v[162:163], 0, s[80:81]
	v_xor_b32_e32 v165, 16, v164
	v_xor_b32_e32 v224, 32, v164
	v_or_b32_e32 v223, s29, v235
	v_lshlrev_b32_e32 v165, 2, v165
	v_lshlrev_b32_e32 v224, 2, v224
	v_lshl_add_u32 v222, v223, 4, s3
	v_cmp_gt_u32_e64 s[12:13], 16, v164
	s_waitcnt vmcnt(12)
	v_pk_fma_f32 v[126:127], v[126:127], v[142:143], v[146:147]
	v_pk_fma_f32 v[128:129], v[128:129], v[144:145], v[148:149]
	v_pk_mul_f32 v[226:227], v[126:127], v[126:127]
	v_pk_fma_f32 v[226:227], v[128:129], v[128:129], v[226:227]
	v_pk_fma_f32 v[122:123], v[122:123], v[138:139], v[150:151]
	v_pk_fma_f32 v[124:125], v[124:125], v[140:141], v[152:153]
	v_pk_fma_f32 v[226:227], v[122:123], v[122:123], v[226:227]
	v_pk_fma_f32 v[226:227], v[124:125], v[124:125], v[226:227]
	v_pk_fma_f32 v[110:111], v[110:111], v[134:135], v[154:155]
	v_pk_fma_f32 v[112:113], v[112:113], v[136:137], v[156:157]
	v_pk_fma_f32 v[226:227], v[110:111], v[110:111], v[226:227]
	v_pk_fma_f32 v[226:227], v[112:113], v[112:113], v[226:227]
	v_pk_fma_f32 v[102:103], v[102:103], v[130:131], v[158:159]
	v_pk_fma_f32 v[104:105], v[104:105], v[132:133], v[160:161]
	v_pk_fma_f32 v[226:227], v[102:103], v[102:103], v[226:227]
	v_pk_fma_f32 v[226:227], v[104:105], v[104:105], v[226:227]
	global_load_dwordx4 v[146:149], v[162:163], off nt
	global_load_dwordx4 v[150:153], v[162:163], off offset:64 nt
	global_load_dwordx4 v[154:157], v[162:163], off offset:512 nt
	global_load_dwordx4 v[158:161], v[162:163], off offset:576 nt
	v_lshl_add_u64 v[162:163], v[162:163], 0, s[78:79]
	v_add_f32_e32 v246, v226, v227
	s_waitcnt vmcnt(12)
	v_pk_fma_f32 v[118:119], v[118:119], v[142:143], v[166:167]
	v_pk_fma_f32 v[120:121], v[120:121], v[144:145], v[168:169]
	v_pk_mul_f32 v[226:227], v[118:119], v[118:119]
	v_pk_fma_f32 v[226:227], v[120:121], v[120:121], v[226:227]
	v_pk_fma_f32 v[114:115], v[114:115], v[138:139], v[170:171]
	v_pk_fma_f32 v[116:117], v[116:117], v[140:141], v[172:173]
	v_pk_fma_f32 v[226:227], v[114:115], v[114:115], v[226:227]
	v_pk_fma_f32 v[226:227], v[116:117], v[116:117], v[226:227]
	v_pk_fma_f32 v[94:95], v[94:95], v[134:135], v[174:175]
	v_pk_fma_f32 v[96:97], v[96:97], v[136:137], v[176:177]
	v_pk_fma_f32 v[226:227], v[94:95], v[94:95], v[226:227]
	v_pk_fma_f32 v[226:227], v[96:97], v[96:97], v[226:227]
	v_pk_fma_f32 v[86:87], v[86:87], v[130:131], v[178:179]
	v_pk_fma_f32 v[88:89], v[88:89], v[132:133], v[180:181]
	v_pk_fma_f32 v[226:227], v[86:87], v[86:87], v[226:227]
	v_pk_fma_f32 v[226:227], v[88:89], v[88:89], v[226:227]
	global_load_dwordx4 v[166:169], v[162:163], off nt
	global_load_dwordx4 v[170:173], v[162:163], off offset:64 nt
	global_load_dwordx4 v[174:177], v[162:163], off offset:512 nt
	global_load_dwordx4 v[178:181], v[162:163], off offset:576 nt
	v_lshl_add_u64 v[162:163], v[162:163], 0, s[78:79]
	v_add_f32_e32 v247, v226, v227
	s_waitcnt vmcnt(12)
;     static __device__ __forceinline__ f32x4 ldb(const void* base, size_t idx) { if (MODE == 0) return *(const f32x4*)((const float*)base + idx); const u32x2 w = *(const u32x2*)((const bf16_t*)base + idx); return (f32x4){bflo(w.x), bfhi(w.x), bflo(w.y), bfhi(w.y)}; }
;     __device__ __forceinline__ void operator()(const f32x4 (&acc)[2][2][4][2], const Unit& u, int wr, int wc, int fr, int fq) const {
;     ...
;         for (int ai = 0; ai < 2; ++ai)
; #pragma unroll
;           for (int mp = 0; mp < 2; ++mp) { f32x4 bb[2][2][2];
; #pragma unroll
;             for (int mm = 0; mm < 2; ++mm) { const size_t bi = (size_t)(row0 + ai * HALF + (2 * mp + mm) * 16) * DM + col0;
; #pragma unroll
;                 for (int bj = 0; bj < 2; ++bj)
; #pragma unroll
;                     for (int n = 0; n < 2; ++n) bb[mm][bj][n] = ldb(baseP, bi + bj * HALF + n * 16); }
; #pragma unroll
;             for (int mm = 0; mm < 2; ++mm) { const int m = 2 * mp + mm; float s = 0.f;
; #pragma unroll
;                 for (int bj = 0; bj < 2; ++bj)
; #pragma unroll
;                     for (int n = 0; n < 2; ++n) { const f32x4 x = bb[mm][bj][n] + gt[bj][n] * acc[ai][bj][m][n]; s += (x[0] * x[0] + x[1] * x[1]) + (x[2] * x[2] + x[3] * x[3]); }
;                 s += __shfl_xor(s, 16); s += __shfl_xor(s, 32);
;                 if (fq == 0) P[(ai * HALF + wr * 64 + m * 16 + fr) * 4 + wc] = s; }
;             asm volatile("" ::: "memory"); }
	v_pk_fma_f32 v[106:107], v[106:107], v[142:143], v[182:183]
	v_pk_fma_f32 v[108:109], v[108:109], v[144:145], v[184:185]
	v_pk_mul_f32 v[226:227], v[106:107], v[106:107]
	v_pk_fma_f32 v[226:227], v[108:109], v[108:109], v[226:227]
	v_pk_fma_f32 v[98:99], v[98:99], v[138:139], v[202:203]
	v_pk_fma_f32 v[100:101], v[100:101], v[140:141], v[204:205]
	v_pk_fma_f32 v[226:227], v[98:99], v[98:99], v[226:227]
	v_pk_fma_f32 v[226:227], v[100:101], v[100:101], v[226:227]
	v_pk_fma_f32 v[78:79], v[78:79], v[134:135], v[206:207]
	v_pk_fma_f32 v[80:81], v[80:81], v[136:137], v[208:209]
	v_pk_fma_f32 v[226:227], v[78:79], v[78:79], v[226:227]
	v_pk_fma_f32 v[226:227], v[80:81], v[80:81], v[226:227]
	v_pk_fma_f32 v[74:75], v[74:75], v[130:131], v[210:211]
	v_pk_fma_f32 v[76:77], v[76:77], v[132:133], v[212:213]
	v_pk_fma_f32 v[226:227], v[74:75], v[74:75], v[226:227]
	v_pk_fma_f32 v[226:227], v[76:77], v[76:77], v[226:227]
	global_load_dwordx4 v[182:185], v[162:163], off nt
	global_load_dwordx4 v[202:205], v[162:163], off offset:64 nt
	global_load_dwordx4 v[206:209], v[162:163], off offset:512 nt
	global_load_dwordx4 v[210:213], v[162:163], off offset:576 nt
	v_lshl_add_u64 v[162:163], v[162:163], 0, s[78:79]
	v_add_f32_e32 v248, v226, v227
	s_waitcnt vmcnt(12)
	v_pk_fma_f32 v[90:91], v[90:91], v[142:143], v[214:215]
	v_pk_fma_f32 v[92:93], v[92:93], v[144:145], v[216:217]
	v_pk_mul_f32 v[226:227], v[90:91], v[90:91]
	v_pk_fma_f32 v[226:227], v[92:93], v[92:93], v[226:227]
	v_pk_fma_f32 v[82:83], v[82:83], v[138:139], v[218:219]
	v_pk_fma_f32 v[84:85], v[84:85], v[140:141], v[220:221]
	v_pk_fma_f32 v[226:227], v[82:83], v[82:83], v[226:227]
	v_pk_fma_f32 v[226:227], v[84:85], v[84:85], v[226:227]
	v_pk_fma_f32 v[70:71], v[70:71], v[134:135], v[238:239]
	v_pk_fma_f32 v[72:73], v[72:73], v[136:137], v[240:241]
	v_pk_fma_f32 v[226:227], v[70:71], v[70:71], v[226:227]
	v_pk_fma_f32 v[226:227], v[72:73], v[72:73], v[226:227]
	v_pk_fma_f32 v[66:67], v[66:67], v[130:131], v[242:243]
	v_pk_fma_f32 v[68:69], v[68:69], v[132:133], v[244:245]
	v_pk_fma_f32 v[226:227], v[66:67], v[66:67], v[226:227]
	v_pk_fma_f32 v[226:227], v[68:69], v[68:69], v[226:227]
	global_load_dwordx4 v[214:217], v[162:163], off nt
	global_load_dwordx4 v[218:221], v[162:163], off offset:64 nt
	global_load_dwordx4 v[238:241], v[162:163], off offset:512 nt
	global_load_dwordx4 v[242:245], v[162:163], off offset:576 nt
	v_add_f32_e32 v249, v226, v227
	s_waitcnt vmcnt(12)
	v_pk_fma_f32 v[62:63], v[62:63], v[142:143], v[146:147]
	v_pk_fma_f32 v[64:65], v[64:65], v[144:145], v[148:149]
	v_pk_mul_f32 v[226:227], v[62:63], v[62:63]
	v_pk_fma_f32 v[226:227], v[64:65], v[64:65], v[226:227]
	v_pk_fma_f32 v[58:59], v[58:59], v[138:139], v[150:151]
	v_pk_fma_f32 v[60:61], v[60:61], v[140:141], v[152:153]
	v_pk_fma_f32 v[226:227], v[58:59], v[58:59], v[226:227]
	v_pk_fma_f32 v[226:227], v[60:61], v[60:61], v[226:227]
	v_pk_fma_f32 v[46:47], v[46:47], v[134:135], v[154:155]
	v_pk_fma_f32 v[48:49], v[48:49], v[136:137], v[156:157]
	v_pk_fma_f32 v[226:227], v[46:47], v[46:47], v[226:227]
	v_pk_fma_f32 v[226:227], v[48:49], v[48:49], v[226:227]
	v_pk_fma_f32 v[38:39], v[38:39], v[130:131], v[158:159]
	v_pk_fma_f32 v[40:41], v[40:41], v[132:133], v[160:161]
	v_pk_fma_f32 v[226:227], v[38:39], v[38:39], v[226:227]
	v_pk_fma_f32 v[226:227], v[40:41], v[40:41], v[226:227]
	v_add_f32_e32 v146, v226, v227
	s_waitcnt vmcnt(8)
	v_pk_fma_f32 v[54:55], v[54:55], v[142:143], v[166:167]
	v_pk_fma_f32 v[56:57], v[56:57], v[144:145], v[168:169]
	v_pk_mul_f32 v[226:227], v[54:55], v[54:55]
	v_pk_fma_f32 v[226:227], v[56:57], v[56:57], v[226:227]
	v_pk_fma_f32 v[50:51], v[50:51], v[138:139], v[170:171]
	v_pk_fma_f32 v[52:53], v[52:53], v[140:141], v[172:173]
	v_pk_fma_f32 v[226:227], v[50:51], v[50:51], v[226:227]
	v_pk_fma_f32 v[226:227], v[52:53], v[52:53], v[226:227]
	v_pk_fma_f32 v[30:31], v[30:31], v[134:135], v[174:175]
	v_pk_fma_f32 v[32:33], v[32:33], v[136:137], v[176:177]
	v_pk_fma_f32 v[226:227], v[30:31], v[30:31], v[226:227]
	v_pk_fma_f32 v[226:227], v[32:33], v[32:33], v[226:227]
	v_pk_fma_f32 v[22:23], v[22:23], v[130:131], v[178:179]
	v_pk_fma_f32 v[24:25], v[24:25], v[132:133], v[180:181]
	v_pk_fma_f32 v[226:227], v[22:23], v[22:23], v[226:227]
	v_pk_fma_f32 v[226:227], v[24:25], v[24:25], v[226:227]
	v_add_f32_e32 v166, v226, v227
	s_waitcnt vmcnt(4)
; #define PG8_LAS __attribute__((address_space(3)))
;     __device__ __forceinline__ void operator()(const f32x4 (&acc)[2][2][4][2], const Unit& u, int wr, int wc, int fr, int fq) const {
;     ...
;             for (int mm = 0; mm < 2; ++mm) { const int m = 2 * mp + mm; float s = 0.f;
; #pragma unroll
;                 for (int bj = 0; bj < 2; ++bj)
; #pragma unroll
;                     for (int n = 0; n < 2; ++n) { const f32x4 x = bb[mm][bj][n] + gt[bj][n] * acc[ai][bj][m][n]; s += (x[0] * x[0] + x[1] * x[1]) + (x[2] * x[2] + x[3] * x[3]); }
;                 s += __shfl_xor(s, 16); s += __shfl_xor(s, 32);
;                 if (fq == 0) P[(ai * HALF + wr * 64 + m * 16 + fr) * 4 + wc] = s; }
;             asm volatile("" ::: "memory"); }
;         asm volatile("s_waitcnt lgkmcnt(0)" ::: "memory"); __builtin_amdgcn_s_barrier(); asm volatile("" ::: "memory");
;         const int tid = (wr * 4 + wc) * 64 + fq * 16 + fr;
;         if (tid < 256) { const f32x4 p = *(const PG8_LAS f32x4*)(P + tid * 4); __hip_atomic_store(ssq + (size_t)(u.pm * BM + tid) * 4 + u.pn, (p[0] + p[1]) + (p[2] + p[3]), __ATOMIC_RELAXED, __HIP_MEMORY_SCOPE_AGENT); }
	v_pk_fma_f32 v[42:43], v[42:43], v[142:143], v[182:183]
	v_pk_fma_f32 v[44:45], v[44:45], v[144:145], v[184:185]
	v_pk_mul_f32 v[226:227], v[42:43], v[42:43]
	v_pk_fma_f32 v[226:227], v[44:45], v[44:45], v[226:227]
	v_pk_fma_f32 v[34:35], v[34:35], v[138:139], v[202:203]
	v_pk_fma_f32 v[36:37], v[36:37], v[140:141], v[204:205]
	v_pk_fma_f32 v[226:227], v[34:35], v[34:35], v[226:227]
	v_pk_fma_f32 v[226:227], v[36:37], v[36:37], v[226:227]
	v_pk_fma_f32 v[14:15], v[14:15], v[134:135], v[206:207]
	v_pk_fma_f32 v[16:17], v[16:17], v[136:137], v[208:209]
	v_pk_fma_f32 v[226:227], v[14:15], v[14:15], v[226:227]
	v_pk_fma_f32 v[226:227], v[16:17], v[16:17], v[226:227]
	v_pk_fma_f32 v[10:11], v[10:11], v[130:131], v[210:211]
	v_pk_fma_f32 v[12:13], v[12:13], v[132:133], v[212:213]
	v_pk_fma_f32 v[226:227], v[10:11], v[10:11], v[226:227]
	v_pk_fma_f32 v[226:227], v[12:13], v[12:13], v[226:227]
	v_add_f32_e32 v182, v226, v227
	s_waitcnt vmcnt(0)
	v_pk_fma_f32 v[26:27], v[26:27], v[142:143], v[214:215]
	v_pk_fma_f32 v[28:29], v[28:29], v[144:145], v[216:217]
	v_pk_mul_f32 v[226:227], v[26:27], v[26:27]
	v_pk_fma_f32 v[226:227], v[28:29], v[28:29], v[226:227]
	v_pk_fma_f32 v[18:19], v[18:19], v[138:139], v[218:219]
	v_pk_fma_f32 v[20:21], v[20:21], v[140:141], v[220:221]
	v_pk_fma_f32 v[226:227], v[18:19], v[18:19], v[226:227]
	v_pk_fma_f32 v[226:227], v[20:21], v[20:21], v[226:227]
	v_pk_fma_f32 v[6:7], v[6:7], v[134:135], v[238:239]
	v_pk_fma_f32 v[8:9], v[8:9], v[136:137], v[240:241]
	v_pk_fma_f32 v[226:227], v[6:7], v[6:7], v[226:227]
	v_pk_fma_f32 v[226:227], v[8:9], v[8:9], v[226:227]
	v_pk_fma_f32 v[2:3], v[2:3], v[130:131], v[242:243]
	v_pk_fma_f32 v[4:5], v[4:5], v[132:133], v[244:245]
	v_pk_fma_f32 v[226:227], v[2:3], v[2:3], v[226:227]
	v_pk_fma_f32 v[226:227], v[4:5], v[4:5], v[226:227]
	v_add_f32_e32 v214, v226, v227
	ds_bpermute_b32 v150, v165, v246
	ds_bpermute_b32 v170, v165, v247
	ds_bpermute_b32 v202, v165, v248
	ds_bpermute_b32 v218, v165, v249
	ds_bpermute_b32 v154, v165, v146
	ds_bpermute_b32 v174, v165, v166
	ds_bpermute_b32 v206, v165, v182
	ds_bpermute_b32 v238, v165, v214
	s_waitcnt lgkmcnt(0)
	v_add_f32_e32 v246, v246, v150
	v_add_f32_e32 v247, v247, v170
	v_add_f32_e32 v248, v248, v202
	v_add_f32_e32 v249, v249, v218
	v_add_f32_e32 v146, v146, v154
	v_add_f32_e32 v166, v166, v174
	v_add_f32_e32 v182, v182, v206
	v_add_f32_e32 v214, v214, v238
	ds_bpermute_b32 v150, v224, v246
	ds_bpermute_b32 v170, v224, v247
	ds_bpermute_b32 v202, v224, v248
	ds_bpermute_b32 v218, v224, v249
	ds_bpermute_b32 v154, v224, v146
	ds_bpermute_b32 v174, v224, v166
	ds_bpermute_b32 v206, v224, v182
	ds_bpermute_b32 v238, v224, v214
	s_waitcnt lgkmcnt(0)
	v_add_f32_e32 v246, v246, v150
	v_add_f32_e32 v247, v247, v170
	v_add_f32_e32 v248, v248, v202
	v_add_f32_e32 v249, v249, v218
	v_add_f32_e32 v146, v146, v154
	v_add_f32_e32 v166, v166, v174
	v_add_f32_e32 v182, v182, v206
	v_add_f32_e32 v214, v214, v238
	s_and_saveexec_b64 s[82:83], s[12:13]
	ds_write_b32 v222, v246
	ds_write_b32 v222, v247 offset:256
	ds_write_b32 v222, v248 offset:512
	ds_write_b32 v222, v249 offset:768
	ds_write_b32 v222, v146 offset:2048
	ds_write_b32 v222, v166 offset:2304
	ds_write_b32 v222, v182 offset:2560
	ds_write_b32 v222, v214 offset:2816
	s_or_b64 exec, exec, s[82:83]
	v_and_b32_e32 v146, -16, v164
	s_waitcnt lgkmcnt(0)
	v_or_b32_e32 v147, s43, v235
	s_waitcnt lgkmcnt(0)
	s_barrier
	v_add_u32_e32 v148, v147, v146
	s_movk_i32 s8, 0x100
	v_add_u32_e32 v146, s47, v148
	v_cmp_gt_i32_e64 s[12:13], s8, v148
	v_ashrrev_i32_e32 v147, 31, v146
	s_and_saveexec_b64 s[78:79], s[12:13]
	s_cbranch_execz .LBB0_1303
	v_lshl_add_u32 v149, v148, 4, 0
	v_add_u32_e32 v149, 0x20400, v149
	ds_read_b128 v[150:153], v149
	v_lshl_add_u64 v[154:155], v[146:147], 4, s[52:53]
	s_ashr_i32 s77, s76, 31
	v_lshl_add_u64 v[154:155], s[76:77], 2, v[154:155]
	s_waitcnt lgkmcnt(0)
	v_mov_b32_e32 v156, v151
	v_mov_b32_e32 v157, v152
	v_mov_b32_e32 v151, v153
	v_pk_add_f32 v[150:151], v[156:157], v[150:151]
	s_nop 0
	v_pk_add_f32 v[150:151], v[150:151], v[150:151] op_sel:[0,1] op_sel_hi:[1,0]
	global_store_dword v[154:155], v150, off sc1
